# v12b schedule with the compiler's original exec-masked setprio (all waves same priority), to check how much the static split still contributes
# baseline (speedup 1.0000x reference)
; __device__ __forceinline__ int v_st(int k, int c) { const int kk = (k & ~0xC) | ((k & 4) << 1) | ((k & 8) >> 1); return ((kk >> 3) * 4 + (c >> 5)) * 512 + ((kk & 7) * 32 + (c & 31)) * 2; }
; __device__ __forceinline__ int v_rd_base(int lane) { return ((lane & 3) << 3) | (((lane >> 2) & 3) << 6) | (((lane >> 4) & 1) << 5) | (((lane >> 5) & 1) << 8); }
; #define LBAR() do { asm volatile("s_waitcnt lgkmcnt(0)" ::: "memory"); __builtin_amdgcn_s_barrier(); asm volatile("" ::: "memory"); } while (0)
; __device__ __forceinline__ void attn_unit(const bf16_t* __restrict__ Qb, const bf16_t* __restrict__ Kn, const bf16_t* __restrict__ Vh, const bf16_t* __restrict__ Kr,
;                                           bf16_t* GO, int seq, char* lds, const int tid) {
;   const int wid = tid >> 6, lane = tid & 63, r32 = lane & 31, hi = lane >> 5;
;   char* V_lds = lds; char* K_lds = lds + 3 * SHM_V;
;   float* ws = (float*)(lds + 3 * SHM_V + 3 * SHM_K) + wid * 64; float* li_l = ws; float* al_l = ws + 32;
;   if (wid < 4) __builtin_amdgcn_s_setprio(2); else __builtin_amdgcn_s_setprio(0);
;   float m_reg = -1e30f, l_reg = 0; f32x16 o[4] = {}; bf16x8 qr[8];
;   char* qrl = lds + 3 * SHM_V + 3 * SHM_K + NW * 64 * 4 + wid * 4096 + r32 * 128;
;   const bf16_t* Qw = Qb + (long)(wid * QBLK + r32) * LDQ + hi * 8;
; #pragma unroll
;   for (int d0 = 0; d0 < 8; ++d0) qr[d0] = *reinterpret_cast<const bf16x8*>(Qw + d0 * 16);
; #pragma unroll
;   for (int d0 = 8; d0 < 12; ++d0) *reinterpret_cast<bf16x8*>(qrl + (((2 * (d0 - 8) + hi) ^ ((r32 >> 1) & 7)) << 4)) = *reinterpret_cast<const bf16x8*>(Qw + d0 * 16);
;   const int sr = tid >> 4, sc = (tid & 15) * 8, vst0 = v_st(sr, sc), vst1 = v_st(32 + sr, sc);
;   const int rr = tid >> 3, rc = (tid & 7) * 8;
;   const int vb0 = (int)(uintptr_t)V_lds + v_rd_base(lane);
;   const unsigned offkv = (unsigned)(sr * LDKV + sc) * 2u, offkr = (unsigned)(rr * LDKR + rc) * 2u;
;   struct { bf16x8 vs0, vs1, ks0, ks1, kr; } sr_[1];
;     ...
;   f32x16 pA0, pA1, pB0, pB1; float mnA, mnB, alA, alB; bf16x8 pa0, pa1, pa2, pa3; const int NT = seq / KVBLK;
;     ...
;   SLOAD(0, 0); SWRITE(0, 0); SLOAD(0, KVBLK); LBAR();
.LBB0_1146:
	s_mov_b64 s[18:19], s[0:1]
	s_load_dwordx2 s[30:31], s[26:27], 0x0
	s_waitcnt lgkmcnt(0)
	s_barrier
	s_load_dwordx2 s[38:39], s[18:19], 0x88
	s_mov_b64 s[18:19], s[0:1]
	s_load_dwordx2 s[26:27], s[18:19], 0x88
	s_waitcnt vmcnt(0)
	v_mbcnt_lo_u32_b32 v32, -1, 0
	v_mbcnt_hi_u32_b32 v32, -1, v32
	s_nop 0
	v_add_u32_e32 v33, s7, v32
	v_ashrrev_i32_e32 v0, 6, v33
	v_cmp_lt_i32_e32 vcc, 3, v0
	s_and_saveexec_b64 s[18:19], vcc
	s_xor_b64 s[18:19], exec, s[18:19]
	s_setprio 0
	s_andn2_saveexec_b64 s[18:19], s[18:19]
	s_setprio 2
	s_or_b64 exec, exec, s[18:19]
	s_add_u32 s55, s40, s34
	s_addc_u32 s56, s41, s35
	s_sub_i32 s18, s54, s20
	s_cmp_ge_u32 s54, s20
	s_cselect_b32 s18, s18, s54
	s_xor_b32 s18, s18, s51
	s_sub_i32 s18, s18, s51
	s_ashr_i32 s34, s53, 3
	s_ashr_i32 s35, s34, 31
	s_ashr_i32 s19, s18, 31
	s_and_b32 s51, s53, 7
	s_lshl_b64 s[40:41], s[34:35], s44
	s_lshl_b64 s[18:19], s[18:19], 8
	s_add_u32 s69, s40, s18
	s_addc_u32 s72, s41, s19
	s_add_u32 s53, s30, s28
	s_mul_i32 s18, s72, 0xc00
	s_mul_hi_u32 s19, s69, 0xc00
	s_addc_u32 s54, s31, s29
	s_add_i32 s19, s19, s18
	s_mul_i32 s18, s69, 0xc00
	s_add_u32 s18, s55, s18
	s_addc_u32 s19, s56, s19
	s_mul_i32 s34, s51, 0x180
	s_add_u32 s18, s18, s34
	s_addc_u32 s19, s19, 0
	v_and_b32_e32 v170, 31, v32
	v_lshlrev_b32_e32 v172, 5, v0
	v_bfe_u32 v171, v32, 5, 1
	v_or_b32_e32 v1, v172, v170
	v_mov_b64_e32 v[2:3], s[18:19]
	v_mad_i64_i32 v[2:3], s[18:19], v1, s49, v[2:3]
	v_lshlrev_b32_e32 v164, 4, v171
	v_mov_b32_e32 v165, v193
	v_lshl_add_u64 v[30:31], v[2:3], 0, v[164:165]
	global_load_dwordx4 v[2:5], v[30:31], off offset:256
	global_load_dwordx4 v[6:9], v[30:31], off offset:288
	s_lshl_b64 s[34:35], s[40:41], 12
	s_add_u32 s19, s53, s34
	s_addc_u32 s53, s54, s35
	s_lshl_b32 s18, s51, 9
	s_add_u32 s54, s19, s18
	s_addc_u32 s55, s53, 0
	v_lshlrev_b32_e32 v42, 3, v33
	s_add_u32 s40, s40, s42
	v_and_b32_e32 v18, 0x78, v42
	s_addc_u32 s41, s41, 0
	v_ashrrev_i32_e32 v1, 4, v33
	v_lshlrev_b32_e32 v43, 1, v18
	s_lshl_b64 s[56:57], s[40:41], 7
	s_add_i32 s19, 0, 0x1e000
	s_add_i32 s41, 0, 0x1e800
	v_lshl_or_b32 v68, v1, 12, v43
	v_mov_b32_e32 v69, v193
	v_and_b32_e32 v18, 56, v42
	s_cmp_lg_u32 0, -1
	v_lshl_add_u64 v[72:73], s[54:55], 0, v[68:69]
	v_ashrrev_i32_e32 v44, 3, v33
	s_cselect_b32 s40, 0, 0
	v_lshlrev_b32_e32 v192, 1, v18
	v_add_co_u32_e32 v34, vcc, s79, v72
	s_waitcnt lgkmcnt(0)
	s_add_u32 s38, s38, s56
	v_addc_co_u32_e32 v35, vcc, 0, v73, vcc
	v_lshl_or_b32 v38, v44, 7, v192
	v_mov_b32_e32 v39, v193
	s_addc_u32 s39, s39, s57
	global_load_dwordx4 v[10:13], v[30:31], off offset:320
	global_load_dwordx4 v[14:17], v[30:31], off offset:352
	global_load_dwordx4 v[18:21], v68, s[54:55] offset:256
	global_load_dwordx4 v[22:25], v[34:35], off offset:256
	global_load_dwordx4 v[26:29], v68, s[54:55]
	s_nop 0
	global_load_dwordx4 v[34:37], v[34:35], off
	v_lshl_add_u64 v[70:71], s[38:39], 0, v[38:39]
	s_mov_b32 s38, 0x13000000
	v_add_co_u32_e32 v38, vcc, s38, v70
	v_lshrrev_b32_e32 v45, 1, v33
	s_nop 0
	v_addc_co_u32_e32 v39, vcc, 0, v71, vcc
	global_load_dwordx4 v[38:41], v[38:39], off
	s_nop 0
	global_load_dwordx4 v[124:127], v[30:31], off
	global_load_dwordx4 v[120:123], v[30:31], off offset:32
	global_load_dwordx4 v[116:119], v[30:31], off offset:64
	global_load_dwordx4 v[112:115], v[30:31], off offset:96
	global_load_dwordx4 v[108:111], v[30:31], off offset:128
	global_load_dwordx4 v[104:107], v[30:31], off offset:160
	global_load_dwordx4 v[100:103], v[30:31], off offset:192
	global_load_dwordx4 v[96:99], v[30:31], off offset:224
	v_bfe_u32 v46, v33, 1, 3
	v_bitop3_b32 v47, v45, v171, 7 bitop3:0x6c
	v_lshl_add_u32 v165, v0, 12, s41
	v_bitop3_b32 v48, v171, v46, 2 bitop3:0x36
	v_lshlrev_b32_e32 v47, 4, v47
	v_lshl_add_u32 v0, v170, 7, v165
	v_lshlrev_b32_e32 v48, 4, v48
	v_add_u32_e32 v182, v0, v47
	v_add_u32_e32 v181, v0, v48
	s_mov_b32 s38, 0x13002000
	v_mul_u32_u24_e32 v47, 0x180, v170
	v_or_b32_e32 v80, 0x120, v164
	v_and_b32_e32 v174, 63, v32
	v_lshlrev_b32_e32 v79, 4, v32
	s_mov_b32 s53, s52
	s_mov_b32 s54, s52
	s_mov_b32 s55, s52
	s_waitcnt vmcnt(16)
	ds_write_b128 v182, v[2:5]
	s_waitcnt vmcnt(15)
	ds_write_b128 v181, v[6:9]
	v_bitop3_b32 v2, v171, v46, 4 bitop3:0x36
	v_lshlrev_b32_e32 v2, 4, v2
	v_add_u32_e32 v179, v0, v2
	v_bitop3_b32 v2, v171, v46, 6 bitop3:0x36
	v_lshlrev_b32_e32 v2, 4, v2
	v_add_u32_e32 v177, v0, v2
	v_and_b32_e32 v0, 0xfffff8, v1
	v_lshlrev_b32_e32 v2, 1, v1
	v_and_or_b32 v0, v2, 0, v0
	v_lshrrev_b32_e32 v2, 1, v1
	v_lshrrev_b32_e32 v0, 1, v0
	v_bfe_u32 v3, v42, 5, 2
	v_and_b32_e32 v4, 3, v1
	v_or_b32_e32 v0, v0, v3
	v_and_b32_e32 v2, 7, v1
	v_lshlrev_b32_e32 v0, 9, v0
	v_lshlrev_b32_e32 v2, 6, v2
	v_and_b32_e32 v4, 48, v43
	v_or3_b32 v183, v0, v2, v4
	v_add_u32_e32 v0, 32, v1
	v_and_b32_e32 v5, 0xfffff8, v0
	v_lshlrev_b32_e32 v0, 1, v0
	v_and_or_b32 v0, v0, 0, v5
	v_lshrrev_b32_e32 v0, 1, v0
	v_or_b32_e32 v0, v0, v3
	v_lshlrev_b32_e32 v0, 9, v0
	v_or3_b32 v184, v0, v2, v4
	v_mul_lo_u32 v0, v1, s8
	v_and_b32_e32 v1, 0x70, v45
	v_xad_u32 v185, v43, v1, v0
	v_add_u32_e32 v82, 0, v183
	v_add_u32_e32 v83, 0, v184
	v_add_u32_e32 v0, 0, v185
	s_waitcnt vmcnt(14)
	ds_write_b128 v179, v[10:13]
	s_waitcnt vmcnt(13)
	ds_write_b128 v177, v[14:17]
	s_waitcnt vmcnt(12)
	ds_write_b128 v82, v[18:21]
	s_waitcnt vmcnt(11)
	ds_write_b128 v83, v[22:25]
	s_waitcnt vmcnt(10)
	ds_write_b128 v0, v[26:29] offset:49152
	s_waitcnt vmcnt(9)
	ds_write_b128 v0, v[34:37] offset:61440
	v_mul_lo_u32 v0, v44, s8
	v_or_b32_e32 v1, 0x100, v192
	v_and_b32_e32 v2, 0x70, v33
	v_xad_u32 v186, v1, v2, v0
	v_add_u32_e32 v0, 0, v186
	s_waitcnt vmcnt(8)
	ds_write_b128 v0, v[38:41] offset:49152
	v_add_co_u32_e32 v0, vcc, s84, v72
	v_or_b32_e32 v34, 32, v164
	s_nop 0
	v_addc_co_u32_e32 v1, vcc, 0, v73, vcc
	v_add_co_u32_e32 v2, vcc, s85, v72
	v_lshlrev_b32_e32 v46, 4, v46
	s_nop 0
	v_addc_co_u32_e32 v3, vcc, 0, v73, vcc
	global_load_dwordx4 v[48:51], v[0:1], off offset:256
	global_load_dwordx4 v[52:55], v[0:1], off
	global_load_dwordx4 v[60:63], v[2:3], off offset:256
	global_load_dwordx4 v[56:59], v[2:3], off
	v_add_co_u32_e32 v0, vcc, s38, v70
	v_or_b32_e32 v42, 0x100, v164
	s_nop 0
	v_addc_co_u32_e32 v1, vcc, 0, v71, vcc
	global_load_dwordx4 v[64:67], v[0:1], off
	v_lshlrev_b32_e32 v0, 3, v32
	v_and_b32_e32 v78, 0x70, v0
	v_bitop3_b32 v199, v164, v47, v78 bitop3:0xde
	s_waitcnt lgkmcnt(0)
	s_barrier
; __device__ __forceinline__ void qkt(f32x16& p0, f32x16& p1, const char* Ks, const bf16x8* qr, const char* qrl, int r32, int hi) {
;   p0 = f32x16{}; p1 = f32x16{};
; #pragma unroll
;   for (int d0 = 0; d0 < 8; ++d0) { int cb = (d0 * 16 + hi * 8) * 2;
;     bf16x8 b0 = *reinterpret_cast<const bf16x8*>(Ks + KSWZ(r32, cb));
;     bf16x8 b1 = *reinterpret_cast<const bf16x8*>(Ks + KSWZ(32 + r32, cb));
;     p0 = __builtin_amdgcn_mfma_f32_32x32x16_bf16(b0, qr[d0], p0, 0, 0, 0);
;     p1 = __builtin_amdgcn_mfma_f32_32x32x16_bf16(b1, qr[d0], p1, 0, 0, 0); }
; #pragma unroll
;   for (int d0 = 8; d0 < 12; ++d0) { int cb = (d0 * 16 + hi * 8) * 2;
;     bf16x8 b0 = *reinterpret_cast<const bf16x8*>(Ks + KSWZ(r32, cb));
;     bf16x8 b1 = *reinterpret_cast<const bf16x8*>(Ks + KSWZ(32 + r32, cb));
;     bf16x8 qf = *reinterpret_cast<const bf16x8*>(qrl + (((2 * (d0 - 8) + hi) ^ ((r32 >> 1) & 7)) << 4));
;     p0 = __builtin_amdgcn_mfma_f32_32x32x16_bf16(b0, qf, p0, 0, 0, 0);
;     p1 = __builtin_amdgcn_mfma_f32_32x32x16_bf16(b1, qf, p1, 0, 0, 0); }
; }
	v_add_u32_e32 v4, 0, v199
	ds_read_b128 v[0:3], v4 offset:49152
	ds_read_b128 v[16:19], v4 offset:61440
	s_waitcnt vmcnt(12) lgkmcnt(1)
	v_mfma_f32_32x32x16_bf16 v[0:15], v[0:3], v[124:127], 0
	v_bitop3_b32 v205, v34, v47, v78 bitop3:0xde
	v_add_u32_e32 v38, 0, v205
	ds_read_b128 v[34:37], v38 offset:49152
	ds_read_b128 v[38:41], v38 offset:61440
	v_xad_u32 v191, v42, v46, v47
	v_and_b32_e32 v33, 0x3fffffc0, v33
	v_xad_u32 v202, v42, v78, v47
	v_lshl_add_u32 v173, v33, 2, s19
	s_waitcnt lgkmcnt(2)
	v_mfma_f32_32x32x16_bf16 v[16:31], v[16:19], v[124:127], 0
	v_add_u32_e32 v33, 0, v202
	v_xad_u32 v198, v80, v46, v47
	v_xad_u32 v201, v80, v78, v47
	v_lshlrev_b32_e32 v32, 1, v32
	v_and_b32_e32 v32, 32, v32
	s_mov_b32 s19, 0x13004000
	s_mov_b32 s56, s52
	s_waitcnt vmcnt(11) lgkmcnt(1)
	v_mfma_f32_32x32x16_bf16 v[0:15], v[34:37], v[120:123], v[0:15]
	v_or_b32_e32 v34, 64, v164
	v_bitop3_b32 v206, v34, v47, v78 bitop3:0xde
	s_mov_b32 s57, s52
	s_mov_b32 s58, s52
	s_mov_b32 s59, s52
	s_mov_b32 s60, s52
	s_mov_b32 s61, s52
	s_waitcnt lgkmcnt(0)
	v_mfma_f32_32x32x16_bf16 v[16:31], v[38:41], v[120:123], v[16:31]
	v_add_u32_e32 v38, 0, v206
	ds_read_b128 v[34:37], v38 offset:49152
	ds_read_b128 v[38:41], v38 offset:61440
	s_mov_b32 s62, s52
	s_mov_b32 s63, s52
	s_mov_b32 s64, s52
	s_mov_b32 s65, s52
	s_mov_b32 s66, s52
	s_waitcnt vmcnt(10) lgkmcnt(1)
	v_mfma_f32_32x32x16_bf16 v[0:15], v[34:37], v[116:119], v[0:15]
	v_or_b32_e32 v34, 0x60, v164
	v_bitop3_b32 v208, v34, v47, v78 bitop3:0xde
	s_mov_b32 s67, s52
	s_mov_b32 s73, 2
	s_mov_b32 s76, 1
	v_cmp_gt_u32_e64 s[38:39], 32, v174
	v_lshl_add_u32 v175, v170, 2, v173
	s_waitcnt lgkmcnt(0)
	v_mfma_f32_32x32x16_bf16 v[16:31], v[38:41], v[116:119], v[16:31]
	v_add_u32_e32 v38, 0, v208
	ds_read_b128 v[34:37], v38 offset:49152
	ds_read_b128 v[38:41], v38 offset:61440
	v_mov_b32_e32 v176, 0
	s_waitcnt vmcnt(9) lgkmcnt(1)
	v_mfma_f32_32x32x16_bf16 v[0:15], v[34:37], v[112:115], v[0:15]
	v_or_b32_e32 v34, 0x80, v164
	v_xad_u32 v207, v34, v78, v47
	s_waitcnt lgkmcnt(0)
	v_mfma_f32_32x32x16_bf16 v[16:31], v[38:41], v[112:115], v[16:31]
	v_add_u32_e32 v38, 0, v207
	ds_read_b128 v[34:37], v38 offset:49152
	ds_read_b128 v[38:41], v38 offset:61440
	s_waitcnt vmcnt(8) lgkmcnt(1)
	v_mfma_f32_32x32x16_bf16 v[0:15], v[34:37], v[108:111], v[0:15]
	v_or_b32_e32 v34, 0xa0, v164
	v_xad_u32 v204, v34, v78, v47
	s_waitcnt lgkmcnt(0)
	v_mfma_f32_32x32x16_bf16 v[16:31], v[38:41], v[108:111], v[16:31]
	v_add_u32_e32 v38, 0, v204
	ds_read_b128 v[34:37], v38 offset:49152
	ds_read_b128 v[38:41], v38 offset:61440
	s_waitcnt vmcnt(7) lgkmcnt(1)
	v_mfma_f32_32x32x16_bf16 v[0:15], v[34:37], v[104:107], v[0:15]
	v_or_b32_e32 v34, 0xc0, v164
	v_xad_u32 v203, v34, v78, v47
	s_waitcnt lgkmcnt(0)
	v_mfma_f32_32x32x16_bf16 v[16:31], v[38:41], v[104:107], v[16:31]
	v_add_u32_e32 v38, 0, v203
	ds_read_b128 v[34:37], v38 offset:49152
	ds_read_b128 v[38:41], v38 offset:61440
	s_waitcnt vmcnt(6) lgkmcnt(1)
	v_mfma_f32_32x32x16_bf16 v[0:15], v[34:37], v[100:103], v[0:15]
	v_or_b32_e32 v34, 0xe0, v164
	v_xad_u32 v200, v34, v78, v47
	s_waitcnt lgkmcnt(0)
	v_mfma_f32_32x32x16_bf16 v[16:31], v[38:41], v[100:103], v[16:31]
	v_add_u32_e32 v38, 0, v200
	ds_read_b128 v[34:37], v38 offset:49152
	ds_read_b128 v[38:41], v38 offset:61440
	s_waitcnt vmcnt(5) lgkmcnt(1)
	v_mfma_f32_32x32x16_bf16 v[0:15], v[34:37], v[96:99], v[0:15]
	v_add_u32_e32 v34, 0, v191
	ds_read_b128 v[34:37], v34 offset:49152
	s_waitcnt lgkmcnt(1)
	v_mfma_f32_32x32x16_bf16 v[16:31], v[38:41], v[96:99], v[16:31]
	ds_read_b128 v[38:41], v182
	ds_read_b128 v[42:45], v33 offset:61440
	ds_read_b128 v[74:77], v181
	v_lshlrev_b32_e32 v33, 3, v174
	s_waitcnt lgkmcnt(2)
	v_mfma_f32_32x32x16_bf16 v[0:15], v[34:37], v[38:41], v[0:15]
	v_add_u32_e32 v34, 0, v198
	ds_read_b128 v[34:37], v34 offset:49152
	s_waitcnt lgkmcnt(2)
	v_mfma_f32_32x32x16_bf16 v[16:31], v[42:45], v[38:41], v[16:31]
	v_and_b32_e32 v38, 0xc0, v79
	v_and_or_b32 v42, v33, 24, v38
	v_add_u32_e32 v38, 0, v201
	ds_read_b128 v[38:41], v38 offset:61440
	v_and_b32_e32 v33, 0x100, v33
	v_or3_b32 v32, v42, v32, v33
	v_or_b32_e32 v42, 0x140, v164
	v_xad_u32 v187, v42, v46, v47
	v_add_u32_e32 v178, s40, v32
	v_add_u32_e32 v32, 0, v187
	s_waitcnt lgkmcnt(1)
	v_mfma_f32_32x32x16_bf16 v[0:15], v[34:37], v[74:77], v[0:15]
	ds_read_b128 v[32:35], v32 offset:49152
	v_or_b32_e32 v44, 0x160, v164
	v_xad_u32 v189, v42, v78, v47
	v_xad_u32 v188, v44, v46, v47
	v_xad_u32 v190, v44, v78, v47
	s_mov_b64 s[40:41], 0x13008000
	v_lshl_add_u64 v[166:167], v[70:71], 0, s[40:41]
	s_waitcnt lgkmcnt(1)
	v_mfma_f32_32x32x16_bf16 v[16:31], v[38:41], v[74:77], v[16:31]
	ds_read_b128 v[36:39], v179
	v_add_u32_e32 v40, 0, v189
	ds_read_b128 v[40:43], v40 offset:61440
	ds_read_b128 v[74:77], v177
	s_waitcnt lgkmcnt(2)
	v_mfma_f32_32x32x16_bf16 v[0:15], v[32:35], v[36:39], v[0:15]
	v_add_u32_e32 v32, 0, v188
	ds_read_b128 v[32:35], v32 offset:49152
	s_waitcnt lgkmcnt(2)
	v_mfma_f32_32x32x16_bf16 v[16:31], v[40:43], v[36:39], v[16:31]
	v_add_u32_e32 v36, 0, v190
	ds_read_b128 v[78:81], v36 offset:61440
	s_waitcnt lgkmcnt(1)
	v_mfma_f32_32x32x16_bf16 v[0:15], v[32:35], v[74:77], v[0:15]
	v_mov_b64_e32 v[32:33], s[52:53]
	v_mov_b64_e32 v[46:47], s[66:67]
	v_mov_b64_e32 v[34:35], s[54:55]
	v_mov_b64_e32 v[36:37], s[56:57]
	v_mov_b64_e32 v[38:39], s[58:59]
	v_mov_b64_e32 v[40:41], s[60:61]
	v_mov_b64_e32 v[42:43], s[62:63]
	s_waitcnt lgkmcnt(0)
; #define LBAR() do { asm volatile("s_waitcnt lgkmcnt(0)" ::: "memory"); __builtin_amdgcn_s_barrier(); asm volatile("" ::: "memory"); } while (0)
; __device__ __forceinline__ void partialSM(f32x16& p0, f32x16& p1, float& m_reg, float& mn, float& alpha) {
;   constexpr float C = SCALE * 1.4426950408889634f;
;   float pmax = p0[0];
; #pragma unroll
;   for (int r = 1; r < 16; ++r) pmax = fmaxf(pmax, p0[r]);
; #pragma unroll
;   for (int r = 0; r < 16; ++r) pmax = fmaxf(pmax, p1[r]);
;   { auto rr = __builtin_amdgcn_permlane32_swap(__float_as_uint(pmax), __float_as_uint(pmax), false, false);
;     pmax = fmaxf(__uint_as_float(rr[0]), __uint_as_float(rr[1])); }
;   if (__builtin_expect(__all(pmax - m_reg <= THR / SCALE), 1)) { mn = m_reg; alpha = 1.f; }
;   else { mn = fmaxf(m_reg, pmax); alpha = __builtin_amdgcn_exp2f((m_reg - mn) * C); m_reg = mn; }
;   float mnC = -mn * C;
; #pragma unroll
;   for (int r = 0; r < 16; ++r) p0[r] = fmaf(p0[r], C, mnC);
; #pragma unroll
;   for (int r = 0; r < 16; ++r) p1[r] = fmaf(p1[r], C, mnC);
; #pragma unroll
;   for (int r = 0; r < 16; ++r) p0[r] = __builtin_amdgcn_exp2f(p0[r]);
; }
; __device__ __forceinline__ void attn_unit(const bf16_t* __restrict__ Qb, const bf16_t* __restrict__ Kn, const bf16_t* __restrict__ Vh, const bf16_t* __restrict__ Kr,
;                                           bf16_t* GO, int seq, char* lds, const int tid) {
;     ...
;   SLOAD(0, 0); SWRITE(0, 0); SLOAD(0, KVBLK); LBAR();
;   qkt(pA0, pA1, K_lds, qr, qrl, r32, hi); partialSM(pA0, pA1, m_reg, mnA, alA);
;   SWRITE(1, 0); if (2 < NT) SLOAD(0, 2 * KVBLK); LBAR();
;   int bc = 1;
	v_mfma_f32_32x32x16_bf16 v[16:31], v[78:81], v[74:77], v[16:31]
	s_nop 2
	v_max_f32_e32 v74, v1, v1
	v_max_f32_e32 v75, v0, v0
	v_max_f32_e32 v74, v75, v74
	v_max3_f32 v74, v74, v2, v3
	v_max3_f32 v74, v74, v4, v5
	v_max3_f32 v74, v74, v6, v7
	v_max3_f32 v74, v74, v8, v9
	v_max3_f32 v74, v74, v10, v11
	v_max3_f32 v74, v74, v12, v13
	v_max3_f32 v74, v74, v14, v15
	v_max3_f32 v74, v74, v16, v17
	v_max3_f32 v74, v74, v18, v19
	v_max3_f32 v74, v74, v20, v21
	v_max3_f32 v74, v74, v22, v23
	v_max3_f32 v74, v74, v24, v25
	v_max3_f32 v74, v74, v26, v27
	v_max3_f32 v74, v74, v28, v29
	v_max3_f32 v76, v74, v30, v31
	v_mov_b32_e32 v74, v76
	s_nop 1
	v_permlane32_swap_b32_e32 v76, v74
	v_max_f32_e32 v77, v74, v74
	v_add_co_u32_e32 v74, vcc, s19, v70
	s_add_i32 s19, 0, 0x12000
	s_nop 0
	v_addc_co_u32_e32 v75, vcc, 0, v71, vcc
	global_load_dwordx4 v[128:131], v[74:75], off
	v_add_co_u32_e32 v74, vcc, s14, v72
	v_mov_b64_e32 v[44:45], s[64:65]
	s_nop 0
	v_addc_co_u32_e32 v75, vcc, 0, v73, vcc
	v_add_co_u32_e32 v72, vcc, s9, v72
	s_nop 1
	v_addc_co_u32_e32 v73, vcc, 0, v73, vcc
	global_load_dwordx4 v[132:135], v[74:75], off
	global_load_dwordx4 v[144:147], v[74:75], off offset:256
	global_load_dwordx4 v[136:139], v[72:73], off
	global_load_dwordx4 v[140:143], v[72:73], off offset:256
	v_max_f32_e32 v72, v76, v76
	v_max_f32_e32 v72, v72, v77
	v_add_f32_e32 v73, 0x7149f2ca, v72
	v_cmp_ge_f32_e32 vcc, s15, v73
	s_waitcnt vmcnt(9)
	ds_write_b128 v82, v[48:51] offset:16384
	s_waitcnt vmcnt(7)
	ds_write_b128 v83, v[60:63] offset:16384
	v_add_u32_e32 v48, s19, v185
	ds_write_b128 v48, v[52:55]
	s_waitcnt vmcnt(6)
	ds_write_b128 v48, v[56:59] offset:12288
	v_add_u32_e32 v48, s19, v186
	s_cmp_eq_u64 vcc, exec
	s_waitcnt vmcnt(5)
	ds_write_b128 v48, v[64:67]
	v_max_f32_e32 v49, 0xf149f2ca, v72
	s_cselect_b64 vcc, -1, 0
	v_mov_b32_e32 v48, 0xf149f2ca
	v_cndmask_b32_e32 v210, v49, v48, vcc
	v_mul_f32_e32 v48, 0xbdd53b94, v210
	v_fmamk_f32 v0, v0, 0x3dd53b94, v48
	v_exp_f32_e32 v225, v0
	v_fmamk_f32 v0, v1, 0x3dd53b94, v48
	v_exp_f32_e32 v228, v0
	v_fmamk_f32 v0, v2, 0x3dd53b94, v48
	v_exp_f32_e32 v226, v0
	v_fmamk_f32 v0, v3, 0x3dd53b94, v48
	v_exp_f32_e32 v229, v0
	v_fmamk_f32 v0, v4, 0x3dd53b94, v48
	v_exp_f32_e32 v227, v0
	v_fmamk_f32 v0, v5, 0x3dd53b94, v48
	v_exp_f32_e32 v230, v0
	v_fmamk_f32 v0, v6, 0x3dd53b94, v48
	v_exp_f32_e32 v223, v0
	v_fmamk_f32 v0, v7, 0x3dd53b94, v48
	v_exp_f32_e32 v224, v0
	v_fmamk_f32 v0, v8, 0x3dd53b94, v48
	v_exp_f32_e32 v219, v0
	v_fmamk_f32 v0, v9, 0x3dd53b94, v48
	v_exp_f32_e32 v221, v0
	v_fmamk_f32 v0, v10, 0x3dd53b94, v48
	s_add_u32 s19, s28, s34
	v_pk_fma_f32 v[156:157], v[22:23], s[16:17], v[48:49] op_sel_hi:[1,0,0]
	v_sub_f32_e32 v22, 0xf149f2ca, v49
	v_exp_f32_e32 v220, v0
	v_fmamk_f32 v0, v11, 0x3dd53b94, v48
	s_addc_u32 s28, s29, s35
	v_mul_f32_e32 v22, 0x3dd53b94, v22
	v_exp_f32_e32 v222, v0
	v_fmamk_f32 v0, v12, 0x3dd53b94, v48
	s_add_u32 s18, s19, s18
	v_exp_f32_e32 v22, v22
	v_exp_f32_e32 v215, v0
	v_fmamk_f32 v0, v13, 0x3dd53b94, v48
	s_addc_u32 s19, s28, 0
	v_pk_fma_f32 v[148:149], v[30:31], s[16:17], v[48:49] op_sel_hi:[1,0,0]
	v_pk_fma_f32 v[150:151], v[28:29], s[16:17], v[48:49] op_sel_hi:[1,0,0]
	v_pk_fma_f32 v[152:153], v[26:27], s[16:17], v[48:49] op_sel_hi:[1,0,0]
	v_pk_fma_f32 v[154:155], v[24:25], s[16:17], v[48:49] op_sel_hi:[1,0,0]
	v_pk_fma_f32 v[158:159], v[20:21], s[16:17], v[48:49] op_sel_hi:[1,0,0]
	v_pk_fma_f32 v[160:161], v[18:19], s[16:17], v[48:49] op_sel_hi:[1,0,0]
	v_pk_fma_f32 v[162:163], v[16:17], s[16:17], v[48:49] op_sel_hi:[1,0,0]
	v_exp_f32_e32 v217, v0
	v_fmamk_f32 v0, v14, 0x3dd53b94, v48
	v_fmac_f32_e32 v48, 0x3dd53b94, v15
	s_add_u32 s18, s30, s18
	v_exp_f32_e32 v216, v0
	v_exp_f32_e32 v218, v48
	s_addc_u32 s19, s31, s19
	s_waitcnt lgkmcnt(0)
	s_barrier
	v_lshl_add_u64 v[0:1], s[18:19], 0, v[68:69]
	s_mov_b64 s[18:19], 0x120100
	v_cndmask_b32_e64 v209, v22, 1.0, vcc
	v_lshl_add_u64 v[168:169], v[0:1], 0, s[18:19]
	v_mov_b64_e32 v[62:63], v[46:47]
	v_mov_b64_e32 v[16:17], v[32:33]
	v_mov_b64_e32 v[0:1], v[32:33]
	v_mov_b64_e32 v[60:61], v[44:45]
	v_mov_b64_e32 v[58:59], v[42:43]
	v_mov_b64_e32 v[56:57], v[40:41]
	v_mov_b64_e32 v[54:55], v[38:39]
	v_mov_b64_e32 v[52:53], v[36:37]
	v_mov_b64_e32 v[50:51], v[34:35]
	v_mov_b64_e32 v[48:49], v[32:33]
	v_mov_b64_e32 v[18:19], v[34:35]
	v_mov_b64_e32 v[20:21], v[36:37]
	v_mov_b64_e32 v[22:23], v[38:39]
	v_mov_b64_e32 v[24:25], v[40:41]
	v_mov_b64_e32 v[26:27], v[42:43]
	v_mov_b64_e32 v[28:29], v[44:45]
	v_mov_b64_e32 v[30:31], v[46:47]
	v_mov_b64_e32 v[2:3], v[34:35]
	v_mov_b64_e32 v[4:5], v[36:37]
	v_mov_b64_e32 v[6:7], v[38:39]
	v_mov_b64_e32 v[8:9], v[40:41]
	v_mov_b64_e32 v[10:11], v[42:43]
	v_mov_b64_e32 v[12:13], v[44:45]
	v_mov_b64_e32 v[14:15], v[46:47]
	v_add_u32_e32 v199, 0x9000, v199
	v_add_u32_e32 v205, 0x9000, v205
	v_add_u32_e32 v206, 0x9000, v206
	v_add_u32_e32 v208, 0x9000, v208
	v_add_u32_e32 v207, 0x9000, v207
	v_add_u32_e32 v204, 0x9000, v204
	v_add_u32_e32 v203, 0x9000, v203
	v_add_u32_e32 v200, 0x9000, v200
	v_add_u32_e32 v191, 0x9000, v191
	v_add_u32_e32 v198, 0x9000, v198
	v_add_u32_e32 v187, 0x9000, v187
	v_add_u32_e32 v188, 0x9000, v188
	v_add_u32_e32 v202, 0x9000, v202
	v_add_u32_e32 v201, 0x9000, v201
	v_add_u32_e32 v189, 0x9000, v189
	v_add_u32_e32 v190, 0x9000, v190
	v_add_u32_e32 v185, 0x9000, v185
	v_add_u32_e32 v186, 0x9000, v186
